# P7 stage 1a: top-16 of each 64-score half row by a min/max selection network (4x 16-input odd-even merge sort + 3 prune merges) instead of 64 x 16 med3 insertions
# speedup vs baseline: 1.0241x; 1.0005x over previous
; #define LAS __attribute__((address_space(3)))
; __device__ __forceinline__ unsigned orderable(float s) { unsigned u = __builtin_bit_cast(unsigned, s); return (u >> 31) ? ~u : (u | 0x80000000u); }
; __global__ void __launch_bounds__(NTHR, 2) fwd_megakernel(Args a) {
;     ...
;                 const int row = tid & 255, hf = tid >> 8;
;                 unsigned v[16];
; #pragma unroll
;                 for (int j = 0; j < 16; ++j) v[j] = 0u;
;                 const LAS float* sr = SC + row * 129 + hf * 64;
; #pragma unroll 8
;                 for (int k = 0; k < 64; ++k) {
;                     const unsigned uk = (orderable(sr[k]) & ~127u) | (unsigned)(127 - (hf * 64 + k));
.Lcv_nopf_b:
	ds_read2_b32 v[16:17], v24 offset1:1
	ds_read2_b32 v[18:19], v24 offset0:2 offset1:3
	ds_read2_b32 v[20:21], v24 offset0:4 offset1:5
	ds_read2_b32 v[22:23], v24 offset0:6 offset1:7
	ds_read2_b32 v[26:27], v24 offset0:8 offset1:9
	ds_read2_b32 v[28:29], v24 offset0:10 offset1:11
	ds_read2_b32 v[30:31], v24 offset0:12 offset1:13
	ds_read2_b32 v[32:33], v24 offset0:14 offset1:15
	v_add_u32_e32 v25, 0x7f, v85
	s_waitcnt lgkmcnt(7)
	v_ashrrev_i32_e32 v116, 31, v16
	v_or_b32_e32 v116, 0x80000000, v116
	v_xor_b32_e32 v16, v16, v116
	v_and_or_b32 v16, v16, s33, v25
	v_ashrrev_i32_e32 v117, 31, v17
	v_or_b32_e32 v117, 0x80000000, v117
	v_xor_b32_e32 v17, v17, v117
	v_and_or_b32 v17, v17, s33, v25
	v_subrev_u32_e32 v17, 1, v17
	ds_read2_b32 v[34:35], v24 offset0:16 offset1:17
	s_waitcnt lgkmcnt(7)
	v_ashrrev_i32_e32 v118, 31, v18
	v_or_b32_e32 v118, 0x80000000, v118
	v_xor_b32_e32 v18, v18, v118
	v_and_or_b32 v18, v18, s33, v25
	v_subrev_u32_e32 v18, 2, v18
	v_ashrrev_i32_e32 v119, 31, v19
	v_or_b32_e32 v119, 0x80000000, v119
	v_xor_b32_e32 v19, v19, v119
	v_and_or_b32 v19, v19, s33, v25
	v_subrev_u32_e32 v19, 3, v19
	ds_read2_b32 v[36:37], v24 offset0:18 offset1:19
	s_waitcnt lgkmcnt(7)
	v_ashrrev_i32_e32 v116, 31, v20
	v_or_b32_e32 v116, 0x80000000, v116
	v_xor_b32_e32 v20, v20, v116
	v_and_or_b32 v20, v20, s33, v25
	v_subrev_u32_e32 v20, 4, v20
	v_ashrrev_i32_e32 v117, 31, v21
	v_or_b32_e32 v117, 0x80000000, v117
	v_xor_b32_e32 v21, v21, v117
	v_and_or_b32 v21, v21, s33, v25
	v_subrev_u32_e32 v21, 5, v21
	ds_read2_b32 v[38:39], v24 offset0:20 offset1:21
	s_waitcnt lgkmcnt(7)
	v_ashrrev_i32_e32 v118, 31, v22
	v_or_b32_e32 v118, 0x80000000, v118
	v_xor_b32_e32 v22, v22, v118
	v_and_or_b32 v22, v22, s33, v25
	v_subrev_u32_e32 v22, 6, v22
	v_ashrrev_i32_e32 v119, 31, v23
	v_or_b32_e32 v119, 0x80000000, v119
	v_xor_b32_e32 v23, v23, v119
	v_and_or_b32 v23, v23, s33, v25
	v_subrev_u32_e32 v23, 7, v23
	ds_read2_b32 v[40:41], v24 offset0:22 offset1:23
	s_waitcnt lgkmcnt(7)
	v_ashrrev_i32_e32 v116, 31, v26
	v_or_b32_e32 v116, 0x80000000, v116
	v_xor_b32_e32 v26, v26, v116
	v_and_or_b32 v26, v26, s33, v25
	v_subrev_u32_e32 v26, 8, v26
	v_ashrrev_i32_e32 v117, 31, v27
	v_or_b32_e32 v117, 0x80000000, v117
	v_xor_b32_e32 v27, v27, v117
	v_and_or_b32 v27, v27, s33, v25
	v_subrev_u32_e32 v27, 9, v27
	ds_read2_b32 v[42:43], v24 offset0:24 offset1:25
	s_waitcnt lgkmcnt(7)
	v_ashrrev_i32_e32 v118, 31, v28
	v_or_b32_e32 v118, 0x80000000, v118
	v_xor_b32_e32 v28, v28, v118
	v_and_or_b32 v28, v28, s33, v25
	v_subrev_u32_e32 v28, 10, v28
	v_ashrrev_i32_e32 v119, 31, v29
	v_or_b32_e32 v119, 0x80000000, v119
	v_xor_b32_e32 v29, v29, v119
	v_and_or_b32 v29, v29, s33, v25
	v_subrev_u32_e32 v29, 11, v29
	ds_read2_b32 v[44:45], v24 offset0:26 offset1:27
	s_waitcnt lgkmcnt(7)
	v_ashrrev_i32_e32 v116, 31, v30
	v_or_b32_e32 v116, 0x80000000, v116
	v_xor_b32_e32 v30, v30, v116
	v_and_or_b32 v30, v30, s33, v25
	v_subrev_u32_e32 v30, 12, v30
	v_ashrrev_i32_e32 v117, 31, v31
	v_or_b32_e32 v117, 0x80000000, v117
	v_xor_b32_e32 v31, v31, v117
	v_and_or_b32 v31, v31, s33, v25
	v_subrev_u32_e32 v31, 13, v31
	ds_read2_b32 v[46:47], v24 offset0:28 offset1:29
	s_waitcnt lgkmcnt(7)
	v_ashrrev_i32_e32 v118, 31, v32
	v_or_b32_e32 v118, 0x80000000, v118
	v_xor_b32_e32 v32, v32, v118
	v_and_or_b32 v32, v32, s33, v25
	v_subrev_u32_e32 v32, 14, v32
	v_ashrrev_i32_e32 v119, 31, v33
	v_or_b32_e32 v119, 0x80000000, v119
	v_xor_b32_e32 v33, v33, v119
	v_and_or_b32 v33, v33, s33, v25
	v_subrev_u32_e32 v33, 15, v33
	ds_read2_b32 v[48:49], v24 offset0:30 offset1:31
	s_waitcnt lgkmcnt(7)
	v_ashrrev_i32_e32 v116, 31, v34
	v_or_b32_e32 v116, 0x80000000, v116
	v_xor_b32_e32 v34, v34, v116
	v_and_or_b32 v34, v34, s33, v25
	v_subrev_u32_e32 v34, 16, v34
	v_ashrrev_i32_e32 v117, 31, v35
	v_or_b32_e32 v117, 0x80000000, v117
	v_xor_b32_e32 v35, v35, v117
	v_and_or_b32 v35, v35, s33, v25
	v_subrev_u32_e32 v35, 17, v35
	ds_read2_b32 v[50:51], v24 offset0:32 offset1:33
	s_waitcnt lgkmcnt(7)
	v_ashrrev_i32_e32 v118, 31, v36
	v_or_b32_e32 v118, 0x80000000, v118
	v_xor_b32_e32 v36, v36, v118
	v_and_or_b32 v36, v36, s33, v25
	v_subrev_u32_e32 v36, 18, v36
	v_ashrrev_i32_e32 v119, 31, v37
	v_or_b32_e32 v119, 0x80000000, v119
	v_xor_b32_e32 v37, v37, v119
	v_and_or_b32 v37, v37, s33, v25
	v_subrev_u32_e32 v37, 19, v37
	ds_read2_b32 v[52:53], v24 offset0:34 offset1:35
	s_waitcnt lgkmcnt(7)
	v_ashrrev_i32_e32 v116, 31, v38
	v_or_b32_e32 v116, 0x80000000, v116
	v_xor_b32_e32 v38, v38, v116
	v_and_or_b32 v38, v38, s33, v25
	v_subrev_u32_e32 v38, 20, v38
	v_ashrrev_i32_e32 v117, 31, v39
	v_or_b32_e32 v117, 0x80000000, v117
	v_xor_b32_e32 v39, v39, v117
	v_and_or_b32 v39, v39, s33, v25
	v_subrev_u32_e32 v39, 21, v39
	ds_read2_b32 v[54:55], v24 offset0:36 offset1:37
	s_waitcnt lgkmcnt(7)
	v_ashrrev_i32_e32 v118, 31, v40
	v_or_b32_e32 v118, 0x80000000, v118
	v_xor_b32_e32 v40, v40, v118
	v_and_or_b32 v40, v40, s33, v25
	v_subrev_u32_e32 v40, 22, v40
	v_ashrrev_i32_e32 v119, 31, v41
	v_or_b32_e32 v119, 0x80000000, v119
	v_xor_b32_e32 v41, v41, v119
	v_and_or_b32 v41, v41, s33, v25
	v_subrev_u32_e32 v41, 23, v41
	ds_read2_b32 v[56:57], v24 offset0:38 offset1:39
	s_waitcnt lgkmcnt(7)
	v_ashrrev_i32_e32 v116, 31, v42
	v_or_b32_e32 v116, 0x80000000, v116
	v_xor_b32_e32 v42, v42, v116
	v_and_or_b32 v42, v42, s33, v25
	v_subrev_u32_e32 v42, 24, v42
	v_ashrrev_i32_e32 v117, 31, v43
	v_or_b32_e32 v117, 0x80000000, v117
	v_xor_b32_e32 v43, v43, v117
	v_and_or_b32 v43, v43, s33, v25
	v_subrev_u32_e32 v43, 25, v43
	ds_read2_b32 v[58:59], v24 offset0:40 offset1:41
	s_waitcnt lgkmcnt(7)
; __device__ __forceinline__ unsigned orderable(float s) { unsigned u = __builtin_bit_cast(unsigned, s); return (u >> 31) ? ~u : (u | 0x80000000u); }
; __global__ void __launch_bounds__(NTHR, 2) fwd_megakernel(Args a) {
;     ...
;                 for (int k = 0; k < 64; ++k) {
;                     const unsigned uk = (orderable(sr[k]) & ~127u) | (unsigned)(127 - (hf * 64 + k));
	v_ashrrev_i32_e32 v118, 31, v44
	v_or_b32_e32 v118, 0x80000000, v118
	v_xor_b32_e32 v44, v44, v118
	v_and_or_b32 v44, v44, s33, v25
	v_subrev_u32_e32 v44, 26, v44
	v_ashrrev_i32_e32 v119, 31, v45
	v_or_b32_e32 v119, 0x80000000, v119
	v_xor_b32_e32 v45, v45, v119
	v_and_or_b32 v45, v45, s33, v25
	v_subrev_u32_e32 v45, 27, v45
	ds_read2_b32 v[60:61], v24 offset0:42 offset1:43
	s_waitcnt lgkmcnt(7)
	v_ashrrev_i32_e32 v116, 31, v46
	v_or_b32_e32 v116, 0x80000000, v116
	v_xor_b32_e32 v46, v46, v116
	v_and_or_b32 v46, v46, s33, v25
	v_subrev_u32_e32 v46, 28, v46
	v_ashrrev_i32_e32 v117, 31, v47
	v_or_b32_e32 v117, 0x80000000, v117
	v_xor_b32_e32 v47, v47, v117
	v_and_or_b32 v47, v47, s33, v25
	v_subrev_u32_e32 v47, 29, v47
	ds_read2_b32 v[62:63], v24 offset0:44 offset1:45
	s_waitcnt lgkmcnt(7)
	v_ashrrev_i32_e32 v118, 31, v48
	v_or_b32_e32 v118, 0x80000000, v118
	v_xor_b32_e32 v48, v48, v118
	v_and_or_b32 v48, v48, s33, v25
	v_subrev_u32_e32 v48, 30, v48
	v_ashrrev_i32_e32 v119, 31, v49
	v_or_b32_e32 v119, 0x80000000, v119
	v_xor_b32_e32 v49, v49, v119
	v_and_or_b32 v49, v49, s33, v25
	v_subrev_u32_e32 v49, 31, v49
	ds_read2_b32 v[98:99], v24 offset0:46 offset1:47
	s_waitcnt lgkmcnt(7)
	v_ashrrev_i32_e32 v116, 31, v50
	v_or_b32_e32 v116, 0x80000000, v116
	v_xor_b32_e32 v50, v50, v116
	v_and_or_b32 v50, v50, s33, v25
	v_subrev_u32_e32 v50, 32, v50
	v_ashrrev_i32_e32 v117, 31, v51
	v_or_b32_e32 v117, 0x80000000, v117
	v_xor_b32_e32 v51, v51, v117
	v_and_or_b32 v51, v51, s33, v25
	v_subrev_u32_e32 v51, 33, v51
	ds_read2_b32 v[100:101], v24 offset0:48 offset1:49
	s_waitcnt lgkmcnt(7)
	v_ashrrev_i32_e32 v118, 31, v52
	v_or_b32_e32 v118, 0x80000000, v118
	v_xor_b32_e32 v52, v52, v118
	v_and_or_b32 v52, v52, s33, v25
	v_subrev_u32_e32 v52, 34, v52
	v_ashrrev_i32_e32 v119, 31, v53
	v_or_b32_e32 v119, 0x80000000, v119
	v_xor_b32_e32 v53, v53, v119
	v_and_or_b32 v53, v53, s33, v25
	v_subrev_u32_e32 v53, 35, v53
	ds_read2_b32 v[102:103], v24 offset0:50 offset1:51
	s_waitcnt lgkmcnt(7)
	v_ashrrev_i32_e32 v116, 31, v54
	v_or_b32_e32 v116, 0x80000000, v116
	v_xor_b32_e32 v54, v54, v116
	v_and_or_b32 v54, v54, s33, v25
	v_subrev_u32_e32 v54, 36, v54
	v_ashrrev_i32_e32 v117, 31, v55
	v_or_b32_e32 v117, 0x80000000, v117
	v_xor_b32_e32 v55, v55, v117
	v_and_or_b32 v55, v55, s33, v25
	v_subrev_u32_e32 v55, 37, v55
	ds_read2_b32 v[104:105], v24 offset0:52 offset1:53
	s_waitcnt lgkmcnt(7)
	v_ashrrev_i32_e32 v118, 31, v56
	v_or_b32_e32 v118, 0x80000000, v118
	v_xor_b32_e32 v56, v56, v118
	v_and_or_b32 v56, v56, s33, v25
	v_subrev_u32_e32 v56, 38, v56
	v_ashrrev_i32_e32 v119, 31, v57
	v_or_b32_e32 v119, 0x80000000, v119
	v_xor_b32_e32 v57, v57, v119
	v_and_or_b32 v57, v57, s33, v25
	v_subrev_u32_e32 v57, 39, v57
	ds_read2_b32 v[106:107], v24 offset0:54 offset1:55
	s_waitcnt lgkmcnt(7)
	v_ashrrev_i32_e32 v116, 31, v58
	v_or_b32_e32 v116, 0x80000000, v116
	v_xor_b32_e32 v58, v58, v116
	v_and_or_b32 v58, v58, s33, v25
	v_subrev_u32_e32 v58, 40, v58
	v_ashrrev_i32_e32 v117, 31, v59
	v_or_b32_e32 v117, 0x80000000, v117
	v_xor_b32_e32 v59, v59, v117
	v_and_or_b32 v59, v59, s33, v25
	v_subrev_u32_e32 v59, 41, v59
	ds_read2_b32 v[108:109], v24 offset0:56 offset1:57
	s_waitcnt lgkmcnt(7)
	v_ashrrev_i32_e32 v118, 31, v60
	v_or_b32_e32 v118, 0x80000000, v118
	v_xor_b32_e32 v60, v60, v118
	v_and_or_b32 v60, v60, s33, v25
	v_subrev_u32_e32 v60, 42, v60
	v_ashrrev_i32_e32 v119, 31, v61
	v_or_b32_e32 v119, 0x80000000, v119
	v_xor_b32_e32 v61, v61, v119
	v_and_or_b32 v61, v61, s33, v25
	v_subrev_u32_e32 v61, 43, v61
	ds_read2_b32 v[110:111], v24 offset0:58 offset1:59
	s_waitcnt lgkmcnt(7)
	v_ashrrev_i32_e32 v116, 31, v62
	v_or_b32_e32 v116, 0x80000000, v116
	v_xor_b32_e32 v62, v62, v116
	v_and_or_b32 v62, v62, s33, v25
	v_subrev_u32_e32 v62, 44, v62
	v_ashrrev_i32_e32 v117, 31, v63
	v_or_b32_e32 v117, 0x80000000, v117
	v_xor_b32_e32 v63, v63, v117
	v_and_or_b32 v63, v63, s33, v25
	v_subrev_u32_e32 v63, 45, v63
	ds_read2_b32 v[112:113], v24 offset0:60 offset1:61
	s_waitcnt lgkmcnt(7)
	v_ashrrev_i32_e32 v118, 31, v98
	v_or_b32_e32 v118, 0x80000000, v118
	v_xor_b32_e32 v98, v98, v118
	v_and_or_b32 v98, v98, s33, v25
	v_subrev_u32_e32 v98, 46, v98
	v_ashrrev_i32_e32 v119, 31, v99
	v_or_b32_e32 v119, 0x80000000, v119
	v_xor_b32_e32 v99, v99, v119
	v_and_or_b32 v99, v99, s33, v25
	v_subrev_u32_e32 v99, 47, v99
	ds_read2_b32 v[114:115], v24 offset0:62 offset1:63
	s_waitcnt lgkmcnt(7)
	v_ashrrev_i32_e32 v116, 31, v100
	v_or_b32_e32 v116, 0x80000000, v116
	v_xor_b32_e32 v100, v100, v116
	v_and_or_b32 v100, v100, s33, v25
	v_subrev_u32_e32 v100, 48, v100
	v_ashrrev_i32_e32 v117, 31, v101
	v_or_b32_e32 v117, 0x80000000, v117
	v_xor_b32_e32 v101, v101, v117
	v_and_or_b32 v101, v101, s33, v25
	v_subrev_u32_e32 v101, 49, v101
	s_waitcnt lgkmcnt(6)
	v_ashrrev_i32_e32 v118, 31, v102
	v_or_b32_e32 v118, 0x80000000, v118
	v_xor_b32_e32 v102, v102, v118
	v_and_or_b32 v102, v102, s33, v25
	v_subrev_u32_e32 v102, 50, v102
	v_ashrrev_i32_e32 v119, 31, v103
	v_or_b32_e32 v119, 0x80000000, v119
	v_xor_b32_e32 v103, v103, v119
	v_and_or_b32 v103, v103, s33, v25
	v_subrev_u32_e32 v103, 51, v103
	s_waitcnt lgkmcnt(5)
	v_ashrrev_i32_e32 v116, 31, v104
	v_or_b32_e32 v116, 0x80000000, v116
	v_xor_b32_e32 v104, v104, v116
	v_and_or_b32 v104, v104, s33, v25
	v_subrev_u32_e32 v104, 52, v104
	v_ashrrev_i32_e32 v117, 31, v105
	v_or_b32_e32 v117, 0x80000000, v117
	v_xor_b32_e32 v105, v105, v117
	v_and_or_b32 v105, v105, s33, v25
	v_subrev_u32_e32 v105, 53, v105
	s_waitcnt lgkmcnt(4)
; __device__ __forceinline__ unsigned umed3(unsigned a, unsigned b, unsigned c) { unsigned r; asm("v_med3_u32 %0, %1, %2, %3" : "=v"(r) : "v"(a), "v"(b), "v"(c)); return r; }
; __device__ __forceinline__ unsigned orderable(float s) { unsigned u = __builtin_bit_cast(unsigned, s); return (u >> 31) ? ~u : (u | 0x80000000u); }
; __global__ void __launch_bounds__(NTHR, 2) fwd_megakernel(Args a) {
;     ...
;                 for (int k = 0; k < 64; ++k) {
;                     const unsigned uk = (orderable(sr[k]) & ~127u) | (unsigned)(127 - (hf * 64 + k));
; #pragma unroll
;                     for (int j = 15; j >= 1; --j) v[j] = umed3(v[j - 1], v[j], uk);
;                     v[0] = v[0] > uk ? v[0] : uk;
;                 }
	v_ashrrev_i32_e32 v118, 31, v106
	v_or_b32_e32 v118, 0x80000000, v118
	v_xor_b32_e32 v106, v106, v118
	v_and_or_b32 v106, v106, s33, v25
	v_subrev_u32_e32 v106, 54, v106
	v_ashrrev_i32_e32 v119, 31, v107
	v_or_b32_e32 v119, 0x80000000, v119
	v_xor_b32_e32 v107, v107, v119
	v_and_or_b32 v107, v107, s33, v25
	v_subrev_u32_e32 v107, 55, v107
	s_waitcnt lgkmcnt(3)
	v_ashrrev_i32_e32 v116, 31, v108
	v_or_b32_e32 v116, 0x80000000, v116
	v_xor_b32_e32 v108, v108, v116
	v_and_or_b32 v108, v108, s33, v25
	v_subrev_u32_e32 v108, 56, v108
	v_ashrrev_i32_e32 v117, 31, v109
	v_or_b32_e32 v117, 0x80000000, v117
	v_xor_b32_e32 v109, v109, v117
	v_and_or_b32 v109, v109, s33, v25
	v_subrev_u32_e32 v109, 57, v109
	s_waitcnt lgkmcnt(2)
	v_ashrrev_i32_e32 v118, 31, v110
	v_or_b32_e32 v118, 0x80000000, v118
	v_xor_b32_e32 v110, v110, v118
	v_and_or_b32 v110, v110, s33, v25
	v_subrev_u32_e32 v110, 58, v110
	v_ashrrev_i32_e32 v119, 31, v111
	v_or_b32_e32 v119, 0x80000000, v119
	v_xor_b32_e32 v111, v111, v119
	v_and_or_b32 v111, v111, s33, v25
	v_subrev_u32_e32 v111, 59, v111
	s_waitcnt lgkmcnt(1)
	v_ashrrev_i32_e32 v116, 31, v112
	v_or_b32_e32 v116, 0x80000000, v116
	v_xor_b32_e32 v112, v112, v116
	v_and_or_b32 v112, v112, s33, v25
	v_subrev_u32_e32 v112, 60, v112
	v_ashrrev_i32_e32 v117, 31, v113
	v_or_b32_e32 v117, 0x80000000, v117
	v_xor_b32_e32 v113, v113, v117
	v_and_or_b32 v113, v113, s33, v25
	v_subrev_u32_e32 v113, 61, v113
	s_waitcnt lgkmcnt(0)
	v_ashrrev_i32_e32 v118, 31, v114
	v_or_b32_e32 v118, 0x80000000, v118
	v_xor_b32_e32 v114, v114, v118
	v_and_or_b32 v114, v114, s33, v25
	v_subrev_u32_e32 v114, 62, v114
	v_ashrrev_i32_e32 v119, 31, v115
	v_or_b32_e32 v119, 0x80000000, v119
	v_xor_b32_e32 v115, v115, v119
	v_and_or_b32 v115, v115, s33, v25
	v_subrev_u32_e32 v115, 63, v115
	v_max_u32_e32 v120, v16, v17
	v_min_u32_e32 v17, v16, v17
	v_max_u32_e32 v121, v18, v19
	v_min_u32_e32 v19, v18, v19
	v_max_u32_e32 v122, v120, v121
	v_min_u32_e32 v121, v120, v121
	v_max_u32_e32 v123, v17, v19
	v_min_u32_e32 v19, v17, v19
	v_max_u32_e32 v124, v123, v121
	v_min_u32_e32 v121, v123, v121
	v_max_u32_e32 v125, v20, v21
	v_min_u32_e32 v21, v20, v21
	v_max_u32_e32 v126, v22, v23
	v_min_u32_e32 v23, v22, v23
	v_max_u32_e32 v127, v125, v126
	v_min_u32_e32 v126, v125, v126
	v_max_u32_e32 v128, v21, v23
	v_min_u32_e32 v23, v21, v23
	v_max_u32_e32 v129, v128, v126
	v_min_u32_e32 v126, v128, v126
	v_max_u32_e32 v130, v122, v127
	v_min_u32_e32 v127, v122, v127
	v_max_u32_e32 v131, v121, v126
	v_min_u32_e32 v126, v121, v126
	v_max_u32_e32 v132, v131, v127
	v_min_u32_e32 v127, v131, v127
	v_max_u32_e32 v133, v124, v129
	v_min_u32_e32 v129, v124, v129
	v_max_u32_e32 v134, v19, v23
	v_min_u32_e32 v23, v19, v23
	v_max_u32_e32 v135, v134, v129
	v_min_u32_e32 v129, v134, v129
	v_max_u32_e32 v136, v133, v132
	v_min_u32_e32 v132, v133, v132
	v_max_u32_e32 v137, v135, v127
	v_min_u32_e32 v127, v135, v127
	v_max_u32_e32 v138, v129, v126
	v_min_u32_e32 v126, v129, v126
	v_max_u32_e32 v139, v26, v27
	v_min_u32_e32 v27, v26, v27
	v_max_u32_e32 v16, v28, v29
	v_min_u32_e32 v29, v28, v29
	v_max_u32_e32 v18, v139, v16
	v_min_u32_e32 v16, v139, v16
	v_max_u32_e32 v120, v27, v29
	v_min_u32_e32 v29, v27, v29
	v_max_u32_e32 v17, v120, v16
	v_min_u32_e32 v16, v120, v16
	v_max_u32_e32 v123, v30, v31
	v_min_u32_e32 v31, v30, v31
	v_max_u32_e32 v20, v32, v33
	v_min_u32_e32 v33, v32, v33
	v_max_u32_e32 v22, v123, v20
	v_min_u32_e32 v20, v123, v20
	v_max_u32_e32 v125, v31, v33
	v_min_u32_e32 v33, v31, v33
	v_max_u32_e32 v21, v125, v20
	v_min_u32_e32 v20, v125, v20
	v_max_u32_e32 v128, v18, v22
	v_min_u32_e32 v22, v18, v22
	v_max_u32_e32 v122, v16, v20
	v_min_u32_e32 v20, v16, v20
	v_max_u32_e32 v121, v122, v22
	v_min_u32_e32 v22, v122, v22
	v_max_u32_e32 v131, v17, v21
	v_min_u32_e32 v21, v17, v21
	v_max_u32_e32 v124, v29, v33
	v_min_u32_e32 v33, v29, v33
	v_max_u32_e32 v19, v124, v21
	v_min_u32_e32 v21, v124, v21
	v_max_u32_e32 v134, v131, v121
	v_min_u32_e32 v121, v131, v121
	v_max_u32_e32 v133, v19, v22
	v_min_u32_e32 v22, v19, v22
	v_max_u32_e32 v135, v21, v20
	v_min_u32_e32 v20, v21, v20
	v_max_u32_e32 v129, v130, v128
	v_min_u32_e32 v128, v130, v128
	v_max_u32_e32 v26, v127, v22
	v_min_u32_e32 v22, v127, v22
	v_max_u32_e32 v28, v26, v128
	v_min_u32_e32 v128, v26, v128
	v_max_u32_e32 v139, v132, v121
	v_min_u32_e32 v121, v132, v121
	v_max_u32_e32 v27, v126, v20
	v_min_u32_e32 v20, v126, v20
	v_max_u32_e32 v120, v27, v121
	v_min_u32_e32 v121, v27, v121
	v_max_u32_e32 v30, v139, v28
	v_min_u32_e32 v28, v139, v28
	v_max_u32_e32 v32, v120, v128
	v_min_u32_e32 v128, v120, v128
	v_max_u32_e32 v123, v121, v22
	v_min_u32_e32 v22, v121, v22
	v_max_u32_e32 v31, v136, v134
	v_min_u32_e32 v134, v136, v134
	v_max_u32_e32 v125, v138, v135
	v_min_u32_e32 v135, v138, v135
	v_max_u32_e32 v18, v125, v134
	v_min_u32_e32 v134, v125, v134
	v_max_u32_e32 v16, v137, v133
	v_min_u32_e32 v133, v137, v133
	v_max_u32_e32 v122, v23, v33
	v_min_u32_e32 v33, v23, v33
	v_max_u32_e32 v17, v122, v133
	v_min_u32_e32 v133, v122, v133
	v_max_u32_e32 v29, v16, v18
	v_min_u32_e32 v18, v16, v18
	v_max_u32_e32 v124, v17, v134
	v_min_u32_e32 v134, v17, v134
	v_max_u32_e32 v131, v133, v135
	v_min_u32_e32 v135, v133, v135
	v_max_u32_e32 v19, v31, v30
	v_min_u32_e32 v30, v31, v30
	v_max_u32_e32 v21, v29, v28
	v_min_u32_e32 v28, v29, v28
	v_max_u32_e32 v130, v18, v32
	v_min_u32_e32 v32, v18, v32
	v_max_u32_e32 v127, v124, v128
	v_min_u32_e32 v128, v124, v128
	v_max_u32_e32 v26, v134, v123
	v_min_u32_e32 v123, v134, v123
	v_max_u32_e32 v132, v131, v22
	v_min_u32_e32 v22, v131, v22
	v_max_u32_e32 v126, v135, v20
	v_min_u32_e32 v20, v135, v20
; __device__ __forceinline__ unsigned umed3(unsigned a, unsigned b, unsigned c) { unsigned r; asm("v_med3_u32 %0, %1, %2, %3" : "=v"(r) : "v"(a), "v"(b), "v"(c)); return r; }
; __device__ __forceinline__ unsigned orderable(float s) { unsigned u = __builtin_bit_cast(unsigned, s); return (u >> 31) ? ~u : (u | 0x80000000u); }
; __global__ void __launch_bounds__(NTHR, 2) fwd_megakernel(Args a) {
;     ...
;                 for (int k = 0; k < 64; ++k) {
;                     const unsigned uk = (orderable(sr[k]) & ~127u) | (unsigned)(127 - (hf * 64 + k));
; #pragma unroll
;                     for (int j = 15; j >= 1; --j) v[j] = umed3(v[j - 1], v[j], uk);
;                     v[0] = v[0] > uk ? v[0] : uk;
;                 }
	v_max_u32_e32 v27, v34, v35
	v_min_u32_e32 v35, v34, v35
	v_max_u32_e32 v139, v36, v37
	v_min_u32_e32 v37, v36, v37
	v_max_u32_e32 v120, v27, v139
	v_min_u32_e32 v139, v27, v139
	v_max_u32_e32 v121, v35, v37
	v_min_u32_e32 v37, v35, v37
	v_max_u32_e32 v136, v121, v139
	v_min_u32_e32 v139, v121, v139
	v_max_u32_e32 v138, v38, v39
	v_min_u32_e32 v39, v38, v39
	v_max_u32_e32 v125, v40, v41
	v_min_u32_e32 v41, v40, v41
	v_max_u32_e32 v137, v138, v125
	v_min_u32_e32 v125, v138, v125
	v_max_u32_e32 v23, v39, v41
	v_min_u32_e32 v41, v39, v41
	v_max_u32_e32 v122, v23, v125
	v_min_u32_e32 v125, v23, v125
	v_max_u32_e32 v16, v120, v137
	v_min_u32_e32 v137, v120, v137
	v_max_u32_e32 v17, v139, v125
	v_min_u32_e32 v125, v139, v125
	v_max_u32_e32 v133, v17, v137
	v_min_u32_e32 v137, v17, v137
	v_max_u32_e32 v31, v136, v122
	v_min_u32_e32 v122, v136, v122
	v_max_u32_e32 v29, v37, v41
	v_min_u32_e32 v41, v37, v41
	v_max_u32_e32 v18, v29, v122
	v_min_u32_e32 v122, v29, v122
	v_max_u32_e32 v124, v31, v133
	v_min_u32_e32 v133, v31, v133
	v_max_u32_e32 v134, v18, v137
	v_min_u32_e32 v137, v18, v137
	v_max_u32_e32 v131, v122, v125
	v_min_u32_e32 v125, v122, v125
	v_max_u32_e32 v135, v42, v43
	v_min_u32_e32 v43, v42, v43
	v_max_u32_e32 v34, v44, v45
	v_min_u32_e32 v45, v44, v45
	v_max_u32_e32 v36, v135, v34
	v_min_u32_e32 v34, v135, v34
	v_max_u32_e32 v27, v43, v45
	v_min_u32_e32 v45, v43, v45
	v_max_u32_e32 v35, v27, v34
	v_min_u32_e32 v34, v27, v34
	v_max_u32_e32 v121, v46, v47
	v_min_u32_e32 v47, v46, v47
	v_max_u32_e32 v38, v48, v49
	v_min_u32_e32 v49, v48, v49
	v_max_u32_e32 v40, v121, v38
	v_min_u32_e32 v38, v121, v38
	v_max_u32_e32 v138, v47, v49
	v_min_u32_e32 v49, v47, v49
	v_max_u32_e32 v39, v138, v38
	v_min_u32_e32 v38, v138, v38
	v_max_u32_e32 v23, v36, v40
	v_min_u32_e32 v40, v36, v40
	v_max_u32_e32 v120, v34, v38
	v_min_u32_e32 v38, v34, v38
	v_max_u32_e32 v139, v120, v40
	v_min_u32_e32 v40, v120, v40
	v_max_u32_e32 v17, v35, v39
	v_min_u32_e32 v39, v35, v39
	v_max_u32_e32 v136, v45, v49
	v_min_u32_e32 v49, v45, v49
	v_max_u32_e32 v37, v136, v39
	v_min_u32_e32 v39, v136, v39
	v_max_u32_e32 v29, v17, v139
	v_min_u32_e32 v139, v17, v139
	v_max_u32_e32 v31, v37, v40
	v_min_u32_e32 v40, v37, v40
	v_max_u32_e32 v18, v39, v38
	v_min_u32_e32 v38, v39, v38
	v_max_u32_e32 v122, v16, v23
	v_min_u32_e32 v23, v16, v23
	v_max_u32_e32 v42, v137, v40
	v_min_u32_e32 v40, v137, v40
	v_max_u32_e32 v44, v42, v23
	v_min_u32_e32 v23, v42, v23
	v_max_u32_e32 v135, v133, v139
	v_min_u32_e32 v139, v133, v139
	v_max_u32_e32 v43, v125, v38
	v_min_u32_e32 v38, v125, v38
	v_max_u32_e32 v27, v43, v139
	v_min_u32_e32 v139, v43, v139
	v_max_u32_e32 v46, v135, v44
	v_min_u32_e32 v44, v135, v44
	v_max_u32_e32 v48, v27, v23
	v_min_u32_e32 v23, v27, v23
	v_max_u32_e32 v121, v139, v40
	v_min_u32_e32 v40, v139, v40
	v_max_u32_e32 v47, v124, v29
	v_min_u32_e32 v29, v124, v29
	v_max_u32_e32 v138, v131, v18
	v_min_u32_e32 v18, v131, v18
	v_max_u32_e32 v36, v138, v29
	v_min_u32_e32 v29, v138, v29
	v_max_u32_e32 v34, v134, v31
	v_min_u32_e32 v31, v134, v31
	v_max_u32_e32 v120, v41, v49
	v_min_u32_e32 v49, v41, v49
	v_max_u32_e32 v35, v120, v31
	v_min_u32_e32 v31, v120, v31
	v_max_u32_e32 v45, v34, v36
	v_min_u32_e32 v36, v34, v36
	v_max_u32_e32 v136, v35, v29
	v_min_u32_e32 v29, v35, v29
	v_max_u32_e32 v17, v31, v18
	v_min_u32_e32 v18, v31, v18
	v_max_u32_e32 v37, v47, v46
	v_min_u32_e32 v46, v47, v46
	v_max_u32_e32 v39, v45, v44
	v_min_u32_e32 v44, v45, v44
	v_max_u32_e32 v16, v36, v48
	v_min_u32_e32 v48, v36, v48
	v_max_u32_e32 v137, v136, v23
	v_min_u32_e32 v23, v136, v23
	v_max_u32_e32 v42, v29, v121
	v_min_u32_e32 v121, v29, v121
	v_max_u32_e32 v133, v17, v40
	v_min_u32_e32 v40, v17, v40
	v_max_u32_e32 v125, v18, v38
	v_min_u32_e32 v38, v18, v38
	v_max_u32_e32 v43, v50, v51
	v_min_u32_e32 v51, v50, v51
	v_max_u32_e32 v135, v52, v53
	v_min_u32_e32 v53, v52, v53
	v_max_u32_e32 v27, v43, v135
	v_min_u32_e32 v135, v43, v135
	v_max_u32_e32 v139, v51, v53
	v_min_u32_e32 v53, v51, v53
	v_max_u32_e32 v124, v139, v135
	v_min_u32_e32 v135, v139, v135
	v_max_u32_e32 v131, v54, v55
	v_min_u32_e32 v55, v54, v55
	v_max_u32_e32 v138, v56, v57
	v_min_u32_e32 v57, v56, v57
	v_max_u32_e32 v134, v131, v138
	v_min_u32_e32 v138, v131, v138
	v_max_u32_e32 v41, v55, v57
	v_min_u32_e32 v57, v55, v57
	v_max_u32_e32 v120, v41, v138
	v_min_u32_e32 v138, v41, v138
	v_max_u32_e32 v34, v27, v134
	v_min_u32_e32 v134, v27, v134
	v_max_u32_e32 v35, v135, v138
	v_min_u32_e32 v138, v135, v138
	v_max_u32_e32 v31, v35, v134
	v_min_u32_e32 v134, v35, v134
	v_max_u32_e32 v47, v124, v120
	v_min_u32_e32 v120, v124, v120
	v_max_u32_e32 v45, v53, v57
	v_min_u32_e32 v57, v53, v57
	v_max_u32_e32 v36, v45, v120
	v_min_u32_e32 v120, v45, v120
	v_max_u32_e32 v136, v47, v31
	v_min_u32_e32 v31, v47, v31
	v_max_u32_e32 v29, v36, v134
	v_min_u32_e32 v134, v36, v134
	v_max_u32_e32 v17, v120, v138
	v_min_u32_e32 v138, v120, v138
	v_max_u32_e32 v18, v58, v59
	v_min_u32_e32 v59, v58, v59
	v_max_u32_e32 v50, v60, v61
	v_min_u32_e32 v61, v60, v61
	v_max_u32_e32 v52, v18, v50
	v_min_u32_e32 v50, v18, v50
	v_max_u32_e32 v43, v59, v61
	v_min_u32_e32 v61, v59, v61
	v_max_u32_e32 v51, v43, v50
	v_min_u32_e32 v50, v43, v50
	v_max_u32_e32 v139, v62, v63
	v_min_u32_e32 v63, v62, v63
	v_max_u32_e32 v54, v98, v99
	v_min_u32_e32 v99, v98, v99
	v_max_u32_e32 v56, v139, v54
	v_min_u32_e32 v54, v139, v54
	v_max_u32_e32 v131, v63, v99
	v_min_u32_e32 v99, v63, v99
	v_max_u32_e32 v55, v131, v54
	v_min_u32_e32 v54, v131, v54
	v_max_u32_e32 v41, v52, v56
	v_min_u32_e32 v56, v52, v56
	v_max_u32_e32 v27, v50, v54
	v_min_u32_e32 v54, v50, v54
; __device__ __forceinline__ unsigned umed3(unsigned a, unsigned b, unsigned c) { unsigned r; asm("v_med3_u32 %0, %1, %2, %3" : "=v"(r) : "v"(a), "v"(b), "v"(c)); return r; }
; __device__ __forceinline__ unsigned orderable(float s) { unsigned u = __builtin_bit_cast(unsigned, s); return (u >> 31) ? ~u : (u | 0x80000000u); }
; __global__ void __launch_bounds__(NTHR, 2) fwd_megakernel(Args a) {
;     ...
;                 for (int k = 0; k < 64; ++k) {
;                     const unsigned uk = (orderable(sr[k]) & ~127u) | (unsigned)(127 - (hf * 64 + k));
; #pragma unroll
;                     for (int j = 15; j >= 1; --j) v[j] = umed3(v[j - 1], v[j], uk);
;                     v[0] = v[0] > uk ? v[0] : uk;
;                 }
	v_max_u32_e32 v135, v27, v56
	v_min_u32_e32 v56, v27, v56
	v_max_u32_e32 v35, v51, v55
	v_min_u32_e32 v55, v51, v55
	v_max_u32_e32 v124, v61, v99
	v_min_u32_e32 v99, v61, v99
	v_max_u32_e32 v53, v124, v55
	v_min_u32_e32 v55, v124, v55
	v_max_u32_e32 v45, v35, v135
	v_min_u32_e32 v135, v35, v135
	v_max_u32_e32 v47, v53, v56
	v_min_u32_e32 v56, v53, v56
	v_max_u32_e32 v36, v55, v54
	v_min_u32_e32 v54, v55, v54
	v_max_u32_e32 v120, v34, v41
	v_min_u32_e32 v41, v34, v41
	v_max_u32_e32 v58, v134, v56
	v_min_u32_e32 v56, v134, v56
	v_max_u32_e32 v60, v58, v41
	v_min_u32_e32 v41, v58, v41
	v_max_u32_e32 v18, v31, v135
	v_min_u32_e32 v135, v31, v135
	v_max_u32_e32 v59, v138, v54
	v_min_u32_e32 v54, v138, v54
	v_max_u32_e32 v43, v59, v135
	v_min_u32_e32 v135, v59, v135
	v_max_u32_e32 v62, v18, v60
	v_min_u32_e32 v60, v18, v60
	v_max_u32_e32 v98, v43, v41
	v_min_u32_e32 v41, v43, v41
	v_max_u32_e32 v139, v135, v56
	v_min_u32_e32 v56, v135, v56
	v_max_u32_e32 v63, v136, v45
	v_min_u32_e32 v45, v136, v45
	v_max_u32_e32 v131, v17, v36
	v_min_u32_e32 v36, v17, v36
	v_max_u32_e32 v52, v131, v45
	v_min_u32_e32 v45, v131, v45
	v_max_u32_e32 v50, v29, v47
	v_min_u32_e32 v47, v29, v47
	v_max_u32_e32 v27, v57, v99
	v_min_u32_e32 v99, v57, v99
	v_max_u32_e32 v51, v27, v47
	v_min_u32_e32 v47, v27, v47
	v_max_u32_e32 v61, v50, v52
	v_min_u32_e32 v52, v50, v52
	v_max_u32_e32 v124, v51, v45
	v_min_u32_e32 v45, v51, v45
	v_max_u32_e32 v35, v47, v36
	v_min_u32_e32 v36, v47, v36
	v_max_u32_e32 v53, v63, v62
	v_min_u32_e32 v62, v63, v62
	v_max_u32_e32 v55, v61, v60
	v_min_u32_e32 v60, v61, v60
	v_max_u32_e32 v34, v52, v98
	v_min_u32_e32 v98, v52, v98
	v_max_u32_e32 v134, v124, v41
	v_min_u32_e32 v41, v124, v41
	v_max_u32_e32 v58, v45, v139
	v_min_u32_e32 v139, v45, v139
	v_max_u32_e32 v31, v35, v56
	v_min_u32_e32 v56, v35, v56
	v_max_u32_e32 v138, v36, v54
	v_min_u32_e32 v54, v36, v54
	v_max_u32_e32 v59, v100, v101
	v_min_u32_e32 v101, v100, v101
	v_max_u32_e32 v18, v102, v103
	v_min_u32_e32 v103, v102, v103
	v_max_u32_e32 v43, v59, v18
	v_min_u32_e32 v18, v59, v18
	v_max_u32_e32 v135, v101, v103
	v_min_u32_e32 v103, v101, v103
	v_max_u32_e32 v136, v135, v18
	v_min_u32_e32 v18, v135, v18
	v_max_u32_e32 v17, v104, v105
	v_min_u32_e32 v105, v104, v105
	v_max_u32_e32 v131, v106, v107
	v_min_u32_e32 v107, v106, v107
	v_max_u32_e32 v29, v17, v131
	v_min_u32_e32 v131, v17, v131
	v_max_u32_e32 v57, v105, v107
	v_min_u32_e32 v107, v105, v107
	v_max_u32_e32 v27, v57, v131
	v_min_u32_e32 v131, v57, v131
	v_max_u32_e32 v50, v43, v29
	v_min_u32_e32 v29, v43, v29
	v_max_u32_e32 v51, v18, v131
	v_min_u32_e32 v131, v18, v131
	v_max_u32_e32 v47, v51, v29
	v_min_u32_e32 v29, v51, v29
	v_max_u32_e32 v63, v136, v27
	v_min_u32_e32 v27, v136, v27
	v_max_u32_e32 v61, v103, v107
	v_min_u32_e32 v107, v103, v107
	v_max_u32_e32 v52, v61, v27
	v_min_u32_e32 v27, v61, v27
	v_max_u32_e32 v124, v63, v47
	v_min_u32_e32 v47, v63, v47
	v_max_u32_e32 v45, v52, v29
	v_min_u32_e32 v29, v52, v29
	v_max_u32_e32 v35, v27, v131
	v_min_u32_e32 v131, v27, v131
	v_max_u32_e32 v36, v108, v109
	v_min_u32_e32 v109, v108, v109
	v_max_u32_e32 v100, v110, v111
	v_min_u32_e32 v111, v110, v111
	v_max_u32_e32 v102, v36, v100
	v_min_u32_e32 v100, v36, v100
	v_max_u32_e32 v59, v109, v111
	v_min_u32_e32 v111, v109, v111
	v_max_u32_e32 v101, v59, v100
	v_min_u32_e32 v100, v59, v100
	v_max_u32_e32 v135, v112, v113
	v_min_u32_e32 v113, v112, v113
	v_max_u32_e32 v104, v114, v115
	v_min_u32_e32 v115, v114, v115
	v_max_u32_e32 v106, v135, v104
	v_min_u32_e32 v104, v135, v104
	v_max_u32_e32 v17, v113, v115
	v_min_u32_e32 v115, v113, v115
	v_max_u32_e32 v105, v17, v104
	v_min_u32_e32 v104, v17, v104
	v_max_u32_e32 v57, v102, v106
	v_min_u32_e32 v106, v102, v106
	v_max_u32_e32 v43, v100, v104
	v_min_u32_e32 v104, v100, v104
	v_max_u32_e32 v18, v43, v106
	v_min_u32_e32 v106, v43, v106
	v_max_u32_e32 v51, v101, v105
	v_min_u32_e32 v105, v101, v105
	v_max_u32_e32 v136, v111, v115
	v_min_u32_e32 v115, v111, v115
	v_max_u32_e32 v103, v136, v105
	v_min_u32_e32 v105, v136, v105
	v_max_u32_e32 v61, v51, v18
	v_min_u32_e32 v18, v51, v18
	v_max_u32_e32 v63, v103, v106
	v_min_u32_e32 v106, v103, v106
	v_max_u32_e32 v52, v105, v104
	v_min_u32_e32 v104, v105, v104
	v_max_u32_e32 v27, v50, v57
	v_min_u32_e32 v57, v50, v57
	v_max_u32_e32 v108, v29, v106
	v_min_u32_e32 v106, v29, v106
	v_max_u32_e32 v110, v108, v57
	v_min_u32_e32 v57, v108, v57
	v_max_u32_e32 v36, v47, v18
	v_min_u32_e32 v18, v47, v18
	v_max_u32_e32 v109, v131, v104
	v_min_u32_e32 v104, v131, v104
	v_max_u32_e32 v59, v109, v18
	v_min_u32_e32 v18, v109, v18
	v_max_u32_e32 v112, v36, v110
	v_min_u32_e32 v110, v36, v110
	v_max_u32_e32 v114, v59, v57
	v_min_u32_e32 v57, v59, v57
	v_max_u32_e32 v135, v18, v106
	v_min_u32_e32 v106, v18, v106
	v_max_u32_e32 v113, v124, v61
	v_min_u32_e32 v61, v124, v61
	v_max_u32_e32 v17, v35, v52
	v_min_u32_e32 v52, v35, v52
	v_max_u32_e32 v102, v17, v61
	v_min_u32_e32 v61, v17, v61
	v_max_u32_e32 v100, v45, v63
	v_min_u32_e32 v63, v45, v63
	v_max_u32_e32 v43, v107, v115
	v_min_u32_e32 v115, v107, v115
	v_max_u32_e32 v101, v43, v63
	v_min_u32_e32 v63, v43, v63
	v_max_u32_e32 v111, v100, v102
	v_min_u32_e32 v102, v100, v102
	v_max_u32_e32 v136, v101, v61
	v_min_u32_e32 v61, v101, v61
	v_max_u32_e32 v51, v63, v52
	v_min_u32_e32 v52, v63, v52
	v_max_u32_e32 v103, v113, v112
	v_min_u32_e32 v112, v113, v112
	v_max_u32_e32 v105, v111, v110
	v_min_u32_e32 v110, v111, v110
	v_max_u32_e32 v50, v102, v114
	v_min_u32_e32 v114, v102, v114
	v_max_u32_e32 v29, v136, v57
	v_min_u32_e32 v57, v136, v57
	v_max_u32_e32 v108, v61, v135
	v_min_u32_e32 v135, v61, v135
; __device__ __forceinline__ unsigned umed3(unsigned a, unsigned b, unsigned c) { unsigned r; asm("v_med3_u32 %0, %1, %2, %3" : "=v"(r) : "v"(a), "v"(b), "v"(c)); return r; }
; __device__ __forceinline__ unsigned orderable(float s) { unsigned u = __builtin_bit_cast(unsigned, s); return (u >> 31) ? ~u : (u | 0x80000000u); }
; __global__ void __launch_bounds__(NTHR, 2) fwd_megakernel(Args a) {
;     ...
;                 for (int k = 0; k < 64; ++k) {
;                     const unsigned uk = (orderable(sr[k]) & ~127u) | (unsigned)(127 - (hf * 64 + k));
; #pragma unroll
;                     for (int j = 15; j >= 1; --j) v[j] = umed3(v[j - 1], v[j], uk);
;                     v[0] = v[0] > uk ? v[0] : uk;
;                 }
	v_max_u32_e32 v47, v51, v106
	v_min_u32_e32 v106, v51, v106
	v_max_u32_e32 v131, v52, v104
	v_min_u32_e32 v104, v52, v104
	v_max_u32_e32 v129, v129, v49
	v_max_u32_e32 v19, v19, v38
	v_max_u32_e32 v30, v30, v125
	v_max_u32_e32 v21, v21, v40
	v_max_u32_e32 v28, v28, v133
	v_max_u32_e32 v130, v130, v121
	v_max_u32_e32 v32, v32, v42
	v_max_u32_e32 v127, v127, v23
	v_max_u32_e32 v128, v128, v137
	v_max_u32_e32 v26, v26, v48
	v_max_u32_e32 v123, v123, v16
	v_max_u32_e32 v132, v132, v44
	v_max_u32_e32 v22, v22, v39
	v_max_u32_e32 v126, v126, v46
	v_max_u32_e32 v20, v20, v37
	v_max_u32_e32 v33, v33, v122
	v_max_u32_e32 v109, v129, v128
	v_min_u32_e32 v128, v129, v128
	v_max_u32_e32 v36, v19, v26
	v_min_u32_e32 v26, v19, v26
	v_max_u32_e32 v59, v30, v123
	v_min_u32_e32 v123, v30, v123
	v_max_u32_e32 v18, v21, v132
	v_min_u32_e32 v132, v21, v132
	v_max_u32_e32 v124, v28, v22
	v_min_u32_e32 v22, v28, v22
	v_max_u32_e32 v35, v130, v126
	v_min_u32_e32 v126, v130, v126
	v_max_u32_e32 v17, v32, v20
	v_min_u32_e32 v20, v32, v20
	v_max_u32_e32 v45, v127, v33
	v_min_u32_e32 v33, v127, v33
	v_max_u32_e32 v107, v109, v124
	v_min_u32_e32 v124, v109, v124
	v_max_u32_e32 v43, v36, v35
	v_min_u32_e32 v35, v36, v35
	v_max_u32_e32 v100, v59, v17
	v_min_u32_e32 v17, v59, v17
	v_max_u32_e32 v101, v18, v45
	v_min_u32_e32 v45, v18, v45
	v_max_u32_e32 v63, v128, v22
	v_min_u32_e32 v22, v128, v22
	v_max_u32_e32 v113, v26, v126
	v_min_u32_e32 v126, v26, v126
	v_max_u32_e32 v111, v123, v20
	v_min_u32_e32 v20, v123, v20
	v_max_u32_e32 v102, v132, v33
	v_min_u32_e32 v33, v132, v33
	v_max_u32_e32 v136, v107, v100
	v_min_u32_e32 v100, v107, v100
	v_max_u32_e32 v61, v43, v101
	v_min_u32_e32 v101, v43, v101
	v_max_u32_e32 v51, v124, v17
	v_min_u32_e32 v17, v124, v17
	v_max_u32_e32 v52, v35, v45
	v_min_u32_e32 v45, v35, v45
	v_max_u32_e32 v129, v63, v111
	v_min_u32_e32 v111, v63, v111
	v_max_u32_e32 v19, v113, v102
	v_min_u32_e32 v102, v113, v102
	v_max_u32_e32 v30, v22, v20
	v_min_u32_e32 v20, v22, v20
	v_max_u32_e32 v21, v126, v33
	v_min_u32_e32 v33, v126, v33
	v_max_u32_e32 v28, v136, v61
	v_min_u32_e32 v61, v136, v61
	v_max_u32_e32 v130, v100, v101
	v_min_u32_e32 v101, v100, v101
	v_max_u32_e32 v32, v51, v52
	v_min_u32_e32 v52, v51, v52
	v_max_u32_e32 v127, v17, v45
	v_min_u32_e32 v45, v17, v45
	v_max_u32_e32 v109, v129, v19
	v_min_u32_e32 v19, v129, v19
	v_max_u32_e32 v36, v111, v102
	v_min_u32_e32 v102, v111, v102
	v_max_u32_e32 v59, v30, v21
	v_min_u32_e32 v21, v30, v21
	v_max_u32_e32 v18, v20, v33
	v_min_u32_e32 v33, v20, v33
	v_max_u32_e32 v120, v120, v115
	v_max_u32_e32 v53, v53, v104
	v_max_u32_e32 v62, v62, v131
	v_max_u32_e32 v55, v55, v106
	v_max_u32_e32 v60, v60, v47
	v_max_u32_e32 v34, v34, v135
	v_max_u32_e32 v98, v98, v108
	v_max_u32_e32 v134, v134, v57
	v_max_u32_e32 v41, v41, v29
	v_max_u32_e32 v58, v58, v114
	v_max_u32_e32 v139, v139, v50
	v_max_u32_e32 v31, v31, v110
	v_max_u32_e32 v56, v56, v105
	v_max_u32_e32 v138, v138, v112
	v_max_u32_e32 v54, v54, v103
	v_max_u32_e32 v99, v99, v27
	v_max_u32_e32 v128, v120, v41
	v_min_u32_e32 v41, v120, v41
	v_max_u32_e32 v26, v53, v58
	v_min_u32_e32 v58, v53, v58
	v_max_u32_e32 v123, v62, v139
	v_min_u32_e32 v139, v62, v139
	v_max_u32_e32 v132, v55, v31
	v_min_u32_e32 v31, v55, v31
	v_max_u32_e32 v107, v60, v56
	v_min_u32_e32 v56, v60, v56
	v_max_u32_e32 v43, v34, v138
	v_min_u32_e32 v138, v34, v138
	v_max_u32_e32 v124, v98, v54
	v_min_u32_e32 v54, v98, v54
	v_max_u32_e32 v35, v134, v99
	v_min_u32_e32 v99, v134, v99
	v_max_u32_e32 v63, v128, v107
	v_min_u32_e32 v107, v128, v107
	v_max_u32_e32 v113, v26, v43
	v_min_u32_e32 v43, v26, v43
	v_max_u32_e32 v22, v123, v124
	v_min_u32_e32 v124, v123, v124
	v_max_u32_e32 v126, v132, v35
	v_min_u32_e32 v35, v132, v35
	v_max_u32_e32 v136, v41, v56
	v_min_u32_e32 v56, v41, v56
	v_max_u32_e32 v100, v58, v138
	v_min_u32_e32 v138, v58, v138
	v_max_u32_e32 v51, v139, v54
	v_min_u32_e32 v54, v139, v54
	v_max_u32_e32 v17, v31, v99
	v_min_u32_e32 v99, v31, v99
; #define LAS __attribute__((address_space(3)))
; __device__ __forceinline__ unsigned umed3(unsigned a, unsigned b, unsigned c) { unsigned r; asm("v_med3_u32 %0, %1, %2, %3" : "=v"(r) : "v"(a), "v"(b), "v"(c)); return r; }
; __device__ __forceinline__ unsigned orderable(float s) { unsigned u = __builtin_bit_cast(unsigned, s); return (u >> 31) ? ~u : (u | 0x80000000u); }
; __global__ void __launch_bounds__(NTHR, 2) fwd_megakernel(Args a) {
;     ...
;                 for (int k = 0; k < 64; ++k) {
;                     const unsigned uk = (orderable(sr[k]) & ~127u) | (unsigned)(127 - (hf * 64 + k));
; #pragma unroll
;                     for (int j = 15; j >= 1; --j) v[j] = umed3(v[j - 1], v[j], uk);
;                     v[0] = v[0] > uk ? v[0] : uk;
;                 }
;                 if (hf == 1) {
; #pragma unroll
;                     for (int q = 0; q < 4; ++q) *(LAS u32x4*)(KX + row * 16 + 4 * q) = (u32x4){v[4 * q], v[4 * q + 1], v[4 * q + 2], v[4 * q + 3]};
;                 }
	v_max_u32_e32 v129, v63, v22
	v_min_u32_e32 v22, v63, v22
	v_max_u32_e32 v111, v113, v126
	v_min_u32_e32 v126, v113, v126
	v_max_u32_e32 v30, v107, v124
	v_min_u32_e32 v124, v107, v124
	v_max_u32_e32 v20, v43, v35
	v_min_u32_e32 v35, v43, v35
	v_max_u32_e32 v120, v136, v51
	v_min_u32_e32 v51, v136, v51
	v_max_u32_e32 v53, v100, v17
	v_min_u32_e32 v17, v100, v17
	v_max_u32_e32 v62, v56, v54
	v_min_u32_e32 v54, v56, v54
	v_max_u32_e32 v55, v138, v99
	v_min_u32_e32 v99, v138, v99
	v_max_u32_e32 v60, v129, v111
	v_min_u32_e32 v111, v129, v111
	v_max_u32_e32 v34, v22, v126
	v_min_u32_e32 v126, v22, v126
	v_max_u32_e32 v98, v30, v20
	v_min_u32_e32 v20, v30, v20
	v_max_u32_e32 v134, v124, v35
	v_min_u32_e32 v35, v124, v35
	v_max_u32_e32 v128, v120, v53
	v_min_u32_e32 v53, v120, v53
	v_max_u32_e32 v26, v51, v17
	v_min_u32_e32 v17, v51, v17
	v_max_u32_e32 v123, v62, v55
	v_min_u32_e32 v55, v62, v55
	v_max_u32_e32 v132, v54, v99
	v_min_u32_e32 v99, v54, v99
	v_max_u32_e32 v28, v28, v99
	v_max_u32_e32 v61, v61, v132
	v_max_u32_e32 v130, v130, v55
	v_max_u32_e32 v101, v101, v123
	v_max_u32_e32 v32, v32, v17
	v_max_u32_e32 v52, v52, v26
	v_max_u32_e32 v127, v127, v53
	v_max_u32_e32 v45, v45, v128
	v_max_u32_e32 v109, v109, v35
	v_max_u32_e32 v19, v19, v134
	v_max_u32_e32 v36, v36, v20
	v_max_u32_e32 v102, v102, v98
	v_max_u32_e32 v59, v59, v126
	v_max_u32_e32 v21, v21, v34
	v_max_u32_e32 v18, v18, v111
	v_max_u32_e32 v33, v33, v60
	v_max_u32_e32 v41, v28, v109
	v_min_u32_e32 v109, v28, v109
	v_max_u32_e32 v58, v61, v19
	v_min_u32_e32 v19, v61, v19
	v_max_u32_e32 v139, v130, v36
	v_min_u32_e32 v36, v130, v36
	v_max_u32_e32 v31, v101, v102
	v_min_u32_e32 v102, v101, v102
	v_max_u32_e32 v63, v32, v59
	v_min_u32_e32 v59, v32, v59
	v_max_u32_e32 v113, v52, v21
	v_min_u32_e32 v21, v52, v21
	v_max_u32_e32 v107, v127, v18
	v_min_u32_e32 v18, v127, v18
	v_max_u32_e32 v43, v45, v33
	v_min_u32_e32 v33, v45, v33
	v_max_u32_e32 v136, v41, v63
	v_min_u32_e32 v63, v41, v63
	v_max_u32_e32 v100, v58, v113
	v_min_u32_e32 v113, v58, v113
	v_max_u32_e32 v56, v139, v107
	v_min_u32_e32 v107, v139, v107
	v_max_u32_e32 v138, v31, v43
	v_min_u32_e32 v43, v31, v43
	v_max_u32_e32 v129, v109, v59
	v_min_u32_e32 v59, v109, v59
	v_max_u32_e32 v22, v19, v21
	v_min_u32_e32 v21, v19, v21
	v_max_u32_e32 v30, v36, v18
	v_min_u32_e32 v18, v36, v18
	v_max_u32_e32 v124, v102, v33
	v_min_u32_e32 v33, v102, v33
	v_max_u32_e32 v120, v136, v56
	v_min_u32_e32 v56, v136, v56
	v_max_u32_e32 v51, v100, v138
	v_min_u32_e32 v138, v100, v138
	v_max_u32_e32 v62, v63, v107
	v_min_u32_e32 v107, v63, v107
	v_max_u32_e32 v54, v113, v43
	v_min_u32_e32 v43, v113, v43
	v_max_u32_e32 v28, v129, v30
	v_min_u32_e32 v30, v129, v30
	v_max_u32_e32 v61, v22, v124
	v_min_u32_e32 v124, v22, v124
	v_max_u32_e32 v130, v59, v18
	v_min_u32_e32 v18, v59, v18
	v_max_u32_e32 v101, v21, v33
	v_min_u32_e32 v33, v21, v33
	v_max_u32_e32 v32, v120, v51
	v_min_u32_e32 v51, v120, v51
	v_max_u32_e32 v52, v56, v138
	v_min_u32_e32 v138, v56, v138
	v_max_u32_e32 v127, v62, v54
	v_min_u32_e32 v54, v62, v54
	v_max_u32_e32 v45, v107, v43
	v_min_u32_e32 v43, v107, v43
	v_max_u32_e32 v41, v28, v61
	v_min_u32_e32 v61, v28, v61
	v_max_u32_e32 v58, v30, v124
	v_min_u32_e32 v124, v30, v124
	v_max_u32_e32 v139, v130, v101
	v_min_u32_e32 v101, v130, v101
	v_max_u32_e32 v31, v18, v33
	v_min_u32_e32 v33, v18, v33
	v_mov_b32_e32 v0, v32
	v_mov_b32_e32 v1, v51
	v_mov_b32_e32 v2, v52
	v_mov_b32_e32 v3, v138
	v_mov_b32_e32 v4, v127
	v_mov_b32_e32 v5, v54
	v_mov_b32_e32 v6, v45
	v_mov_b32_e32 v7, v43
	v_mov_b32_e32 v8, v41
	v_mov_b32_e32 v9, v61
	v_mov_b32_e32 v10, v58
	v_mov_b32_e32 v11, v124
	v_mov_b32_e32 v12, v139
	v_mov_b32_e32 v13, v101
	v_mov_b32_e32 v14, v31
	v_mov_b32_e32 v15, v33
	s_mov_b32 s44, 0
	s_and_saveexec_b64 s[0:1], s[6:7]
	s_cbranch_execz .LBB0_800
	ds_write_b128 v86, v[0:3]
	ds_write_b128 v86, v[4:7] offset:16
	ds_write_b128 v86, v[8:11] offset:32
	ds_write_b128 v86, v[12:15] offset:48
